# scan2: masks only on the two edge neighbour rows, per-row wait ladder, persistent zero tuples and incremental output address
# speedup vs baseline: 1.0627x; 1.0052x over previous
; #define LAS __attribute__((address_space(3)))
; __device__ __forceinline__ unsigned f2bf(float f) { return pk2(f, f) & 0xffffu; }
; __device__ __forceinline__ void scan2_phase(KA a, LAS unsigned char* lds, int G, const int tid, const int bid) {
;     ...
;             const u32x2 z2 = (u32x2){0u, 0u};
;             bf16x8 sb[2];
; #pragma unroll
;             for (int kb = 0; kb < 2; ++kb) { u32x4 w; w.x = pk2(accS[2 * kb][0], accS[2 * kb][1]); w.y = pk2(accS[2 * kb][2], accS[2 * kb][3]); w.z = pk2(accS[2 * kb + 1][0], accS[2 * kb + 1][1]); w.w = pk2(accS[2 * kb + 1][2], accS[2 * kb + 1][3]); sb[kb] = __builtin_bit_cast(bf16x8, w); }
;             const u32x2 vlo = *(const LAS u32x2*)(VT + (16 * r + fr) * 24 + 4 * fq);
;             f32x4 accX = (f32x4){0.f, 0.f, 0.f, 0.f}, accY = (f32x4){0.f, 0.f, 0.f, 0.f};
; #pragma unroll
;             for (int kb = 0; kb < 2; ++kb) { const u32x2 lo = *(const LAS u32x2*)(At + fr * 72 + 32 * kb + 4 * fq), hi = *(const LAS u32x2*)(At + fr * 72 + 32 * kb + 16 + 4 * fq); accX = __builtin_amdgcn_mfma_f32_16x16x32_bf16(mk8(lo, hi), sb[kb], accX, 0, 0, 0); }
;             { const u32x2 alo = *(const LAS u32x2*)(MkaT + fr * 24 + 4 * fq); accX = __builtin_amdgcn_mfma_f32_16x16x32_bf16(mk8(alo, z2), mk8(vlo, z2), accX, 0, 0, 0); }
; #pragma unroll
;             for (int kb = 0; kb < 2; ++kb) { const u32x2 lo = *(const LAS u32x2*)(Rt + fr * 72 + 32 * kb + 4 * fq), hi = *(const LAS u32x2*)(Rt + fr * 72 + 32 * kb + 16 + 4 * fq); accY = __builtin_amdgcn_mfma_f32_16x16x32_bf16(mk8(lo, hi), sb[kb], accY, 0, 0, 0); }
;             {
;                 f32x4 accSA = (f32x4){0.f, 0.f, 0.f, 0.f};
; #pragma unroll
;                 for (int kk = 0; kk < 4; ++kk) accSA = __builtin_amdgcn_mfma_f32_16x16x4f32(TTf[fr * 20 + 4 * fq + kk], accX[kk], accSA, 0, 0, 0);
;                 u32x2 sav; sav.x = pk2(accSA[0], accSA[1]); sav.y = pk2(accSA[2], accSA[3]);
;                 const bf16x8 bsv = mk8(sav, vlo);
;                 { const u32x2 lo = *(const LAS u32x2*)(MbrT + fr * 24 + 4 * fq), hi = *(const LAS u32x2*)(MkrT + fr * 24 + 4 * fq); accY = __builtin_amdgcn_mfma_f32_16x16x32_bf16(mk8(lo, hi), bsv, accY, 0, 0, 0); }
; #pragma unroll
;                 for (int i = 0; i < 4; ++i) { const int tau = b * 16 + 4 * fq + i; const int t = dir ? len - 1 - tau : tau; Y[(size_t)(row0 + t) * 512 + h * 64 + 16 * r + fr] = (bf16_t)f2bf(accY[i]); }
.Lscs_join:
	s_lshl_b32 s92, s29, 7
	s_mul_i32 s89, s89, 0x1b60
	s_add_u32 s94, s48, s89
	s_addc_u32 s95, s49, 0
	s_add_u32 s94, s94, s92
	s_addc_u32 s95, s95, 0
	s_lshl_b32 s89, s90, 12
	s_add_u32 s96, s4, s89
	s_addc_u32 s97, s5, 0
	s_add_i32 s92, s92, s91
	s_add_u32 s96, s96, s92
	s_addc_u32 s97, s97, 0
	s_lshl_b32 s89, s90, 5
	s_add_u32 s98, s79, s89
	s_addc_u32 s99, s80, 0
	v_mov_b32_e32 v244, 0
	v_mov_b32_e32 v245, 0
	v_mov_b32_e32 v248, 0
	v_mov_b32_e32 v249, 0
	v_add_u32_e32 v250, s77, v143
	v_cndmask_b32_e64 v250, v250, v78, s[8:9]
	v_add_u32_e32 v250, s76, v250
	v_ashrrev_i32_e32 v251, 31, v250
	v_lshlrev_b64 v[250:251], 10, v[250:251]
	v_lshl_add_u64 v[250:251], v[86:87], 0, v[250:251]
	v_mov_b32_e32 v252, 0xfffffc00
	v_mov_b32_e32 v253, 0x400
	v_cndmask_b32_e64 v252, v252, v253, s[8:9]
	v_ashrrev_i32_e32 v253, 31, v252
	s_branch .LBB0_181

; #define LAS __attribute__((address_space(3)))
; __device__ __forceinline__ void scan2_phase(KA a, LAS unsigned char* lds, int G, const int tid, const int bid) {
;     ...
;             const u32x2 z2 = (u32x2){0u, 0u};
;             bf16x8 sb[2];
; #pragma unroll
;             for (int kb = 0; kb < 2; ++kb) { u32x4 w; w.x = pk2(accS[2 * kb][0], accS[2 * kb][1]); w.y = pk2(accS[2 * kb][2], accS[2 * kb][3]); w.z = pk2(accS[2 * kb + 1][0], accS[2 * kb + 1][1]); w.w = pk2(accS[2 * kb + 1][2], accS[2 * kb + 1][3]); sb[kb] = __builtin_bit_cast(bf16x8, w); }
;             const u32x2 vlo = *(const LAS u32x2*)(VT + (16 * r + fr) * 24 + 4 * fq);
;             f32x4 accX = (f32x4){0.f, 0.f, 0.f, 0.f}, accY = (f32x4){0.f, 0.f, 0.f, 0.f};
; #pragma unroll
;             for (int kb = 0; kb < 2; ++kb) { const u32x2 lo = *(const LAS u32x2*)(At + fr * 72 + 32 * kb + 4 * fq), hi = *(const LAS u32x2*)(At + fr * 72 + 32 * kb + 16 + 4 * fq); accX = __builtin_amdgcn_mfma_f32_16x16x32_bf16(mk8(lo, hi), sb[kb], accX, 0, 0, 0); }
;             { const u32x2 alo = *(const LAS u32x2*)(MkaT + fr * 24 + 4 * fq); accX = __builtin_amdgcn_mfma_f32_16x16x32_bf16(mk8(alo, z2), mk8(vlo, z2), accX, 0, 0, 0); }
; #pragma unroll
;             for (int kb = 0; kb < 2; ++kb) { const u32x2 lo = *(const LAS u32x2*)(Rt + fr * 72 + 32 * kb + 4 * fq), hi = *(const LAS u32x2*)(Rt + fr * 72 + 32 * kb + 16 + 4 * fq); accY = __builtin_amdgcn_mfma_f32_16x16x32_bf16(mk8(lo, hi), sb[kb], accY, 0, 0, 0); }
;             {
;                 f32x4 accSA = (f32x4){0.f, 0.f, 0.f, 0.f};
; #pragma unroll
;                 for (int kk = 0; kk < 4; ++kk) accSA = __builtin_amdgcn_mfma_f32_16x16x4f32(TTf[fr * 20 + 4 * fq + kk], accX[kk], accSA, 0, 0, 0);
;                 u32x2 sav; sav.x = pk2(accSA[0], accSA[1]); sav.y = pk2(accSA[2], accSA[3]);
;                 const bf16x8 bsv = mk8(sav, vlo);
;                 { const u32x2 lo = *(const LAS u32x2*)(MbrT + fr * 24 + 4 * fq), hi = *(const LAS u32x2*)(MkrT + fr * 24 + 4 * fq); accY = __builtin_amdgcn_mfma_f32_16x16x32_bf16(mk8(lo, hi), bsv, accY, 0, 0, 0); }
; #pragma unroll
;                 for (int i = 0; i < 4; ++i) { const int tau = b * 16 + 4 * fq + i; const int t = dir ? len - 1 - tau : tau; Y[(size_t)(row0 + t) * 512 + h * 64 + 16 * r + fr] = (bf16_t)f2bf(accY[i]); }
; #pragma unroll
;                 for (int jt = 0; jt < 4; ++jt) {
.LBB0_180:
	v_lshl_add_u32 v52, v78, 1, s84
	s_waitcnt lgkmcnt(0)
	s_barrier
	v_add_u32_e32 v44, v52, v135
	v_add_u32_e32 v16, v52, v91
	ds_read2_b64 v[32:35], v44 offset1:4
	ds_read2_b64 v[36:39], v44 offset0:8 offset1:12
	v_add_u32_e32 v53, v44, v115
	ds_read_b64 v[242:243], v16 offset:15360
	ds_read_b64 v[246:247], v53 offset:18432
	v_add_u32_e32 v40, 0x800, v44
	ds_read2_b64 v[60:63], v40 offset0:32 offset1:36
	ds_read2_b64 v[64:67], v40 offset0:40 offset1:44
	v_lshlrev_b32_e32 v18, 2, v78
	v_add3_u32 v18, s84, v93, v18
	ds_read_b128 v[56:59], v18 offset:22016
	ds_read_b64 v[202:203], v53 offset:19200
	ds_read_b64 v[204:205], v53 offset:19968
	ds_read_b64 v[208:209], v16 offset:15360
	v_cvt_pk_bf16_f32 v20, v12, v13
	v_cvt_pk_bf16_f32 v21, v14, v15
	v_cvt_pk_bf16_f32 v22, v0, v1
	v_cvt_pk_bf16_f32 v23, v2, v3
	v_cvt_pk_bf16_f32 v24, v4, v5
	v_cvt_pk_bf16_f32 v25, v6, v7
	v_cvt_pk_bf16_f32 v26, v8, v9
	v_cvt_pk_bf16_f32 v27, v10, v11
	v_lshl_add_u32 v17, v92, 1, v52
	s_waitcnt lgkmcnt(9)
	v_mfma_f32_16x16x32_bf16 v[32:35], v[32:35], v[20:23], 0
	s_waitcnt lgkmcnt(8)
	v_mfma_f32_16x16x32_bf16 v[32:35], v[36:39], v[24:27], v[32:35]
	s_waitcnt lgkmcnt(5)
	v_mfma_f32_16x16x32_bf16 v[68:71], v[60:63], v[20:23], 0
	v_mfma_f32_16x16x32_bf16 v[32:35], v[246:249], v[242:245], v[32:35]
	s_waitcnt lgkmcnt(4)
	v_mfma_f32_16x16x32_bf16 v[68:71], v[64:67], v[24:27], v[68:71]
	s_waitcnt lgkmcnt(0)
	ds_read_b64 v[210:211], v17 offset:9216
	ds_read_b64 v[212:213], v17 offset:12288
	ds_read_b64 v[214:215], v17 offset:9984
	ds_read_b64 v[216:217], v17 offset:13056
	ds_read_b64 v[218:219], v17 offset:10752
	ds_read_b64 v[220:221], v17 offset:13824
	ds_read_b64 v[222:223], v17 offset:11520
	ds_read_b64 v[224:225], v17 offset:14592
	v_add_u32_e32 v16, v52, v79
	ds_read_b128 v[182:185], v16 offset:23296
	ds_read_b128 v[186:189], v16 offset:23360
	ds_read_b128 v[190:193], v16 offset:23424
	ds_read_b128 v[194:197], v16 offset:23488
	v_mfma_f32_16x16x4_f32 v[72:75], v56, v32, 0
	v_mfma_f32_16x16x4_f32 v[72:75], v57, v33, v[72:75]
	v_mfma_f32_16x16x4_f32 v[72:75], v58, v34, v[72:75]
	v_mfma_f32_16x16x4_f32 v[72:75], v59, v35, v[72:75]
	s_nop 10
	v_cvt_pk_bf16_f32 v206, v72, v73
	v_cvt_pk_bf16_f32 v207, v74, v75
	s_nop 1
	v_mfma_f32_16x16x32_bf16 v[68:71], v[202:205], v[206:209], v[68:71]
	s_waitcnt lgkmcnt(10)
	v_mfma_f32_16x16x32_bf16 v[12:15], v[210:213], v[206:209], v[12:15]
	s_waitcnt lgkmcnt(8)
	v_mfma_f32_16x16x32_bf16 v[0:3], v[214:217], v[206:209], v[0:3]
	s_waitcnt lgkmcnt(6)
	v_mfma_f32_16x16x32_bf16 v[4:7], v[218:221], v[206:209], v[4:7]
	s_waitcnt lgkmcnt(4)
	v_mfma_f32_16x16x32_bf16 v[8:11], v[222:225], v[206:209], v[8:11]
	s_nop 1
	v_cvt_pk_bf16_f32 v24, v68, s0
	global_store_short v[250:251], v24, off
	v_lshl_add_u64 v[16:17], v[250:251], 0, v[252:253]
	v_cvt_pk_bf16_f32 v25, v69, s0
	global_store_short v[16:17], v25, off
	v_lshl_add_u64 v[16:17], v[16:17], 0, v[252:253]
	v_cvt_pk_bf16_f32 v26, v70, s0
	global_store_short v[16:17], v26, off
	v_lshl_add_u64 v[16:17], v[16:17], 0, v[252:253]
	v_cvt_pk_bf16_f32 v27, v71, s0
	global_store_short v[16:17], v27, off
	v_lshl_add_u64 v[250:251], v[252:253], 4, v[250:251]
	s_waitcnt lgkmcnt(0)
	v_pk_mul_f32 v[12:13], v[12:13], v[182:183]
	v_pk_mul_f32 v[14:15], v[14:15], v[184:185]
	v_pk_mul_f32 v[0:1], v[0:1], v[186:187]
	v_pk_mul_f32 v[2:3], v[2:3], v[188:189]
	v_pk_mul_f32 v[4:5], v[4:5], v[190:191]
	v_pk_mul_f32 v[6:7], v[6:7], v[192:193]
	v_pk_mul_f32 v[8:9], v[8:9], v[194:195]
	v_pk_mul_f32 v[10:11], v[10:11], v[196:197]
	s_add_i32 s81, s81, 16
	s_add_i32 s30, s30, -16
	s_cmp_eq_u32 s82, s83
	s_cbranch_scc1 .LBB0_173
.LBB0_181:
	s_bitcmp1_b32 s83, 0
	s_cselect_b32 s29, 0x7000, 0
	s_add_i32 s62, s77, s30
	s_add_i32 s84, s64, s29
	s_add_i32 s29, s66, s81
	s_add_i32 s63, s62, -4
	s_and_b64 s[86:87], s[8:9], exec
	s_cselect_b32 s63, s29, s63
	s_add_i32 s85, s63, -1
	s_cmp_lt_u32 s85, s77
	s_cselect_b64 vcc, -1, 0
	s_waitcnt vmcnt(27)
	v_lshlrev_b32_e32 v16, 16, v124
	v_lshlrev_b32_e32 v17, 16, v125
	v_lshlrev_b32_e32 v18, 16, v126
	v_cndmask_b32_e32 v24, 0, v16, vcc
	v_cndmask_b32_e32 v25, 0, v17, vcc
	v_cndmask_b32_e32 v18, 0, v18, vcc
	s_add_i32 s63, s63, 4
	s_cmp_lt_u32 s63, s77
	s_cselect_b64 vcc, -1, 0
	s_waitcnt vmcnt(24)
	v_lshlrev_b32_e32 v26, 16, v127
	v_lshlrev_b32_e32 v27, 16, v128
	v_lshlrev_b32_e32 v28, 16, v129
	s_waitcnt vmcnt(21)
	v_lshlrev_b32_e32 v29, 16, v130
	v_lshlrev_b32_e32 v30, 16, v131
	v_lshlrev_b32_e32 v31, 16, v136
	s_waitcnt vmcnt(18)
	v_lshlrev_b32_e32 v32, 16, v137
	v_lshlrev_b32_e32 v33, 16, v138
	v_lshlrev_b32_e32 v34, 16, v139
	s_waitcnt vmcnt(13)
	v_lshlrev_b32_e32 v38, 16, v145
	v_lshlrev_b32_e32 v35, 16, v140
	v_lshlrev_b32_e32 v36, 16, v141
	v_lshlrev_b32_e32 v37, 16, v142
	s_waitcnt vmcnt(11)
	v_lshlrev_b32_e32 v39, 16, v150
	s_waitcnt vmcnt(9)
	v_lshlrev_b32_e32 v41, 16, v153
	s_waitcnt vmcnt(6)
	v_lshlrev_b32_e32 v43, 16, v156
	v_add_f32_e32 v40, v38, v39
	v_add_f32_e32 v42, v40, v41
	v_add_f32_e32 v44, v42, v43
	s_add_i32 s63, s84, s69
	v_lshlrev_b32_e32 v16, 2, v77
	v_add_u32_e32 v17, s63, v16
	ds_write_b32 v17, v44 offset:23552
	s_waitcnt lgkmcnt(0)
	s_barrier
; __device__ __forceinline__ unsigned f2bf(float f) { return pk2(f, f) & 0xffffu; }
; __device__ __forceinline__ void scan2_phase(KA a, LAS unsigned char* lds, int G, const int tid, const int bid) {
;     ...
;             float off = 0.f, all = 0.f;
; #pragma unroll
;             for (int w2 = 0; w2 < 4; ++w2) { const float x = tot[w2 * 64 + lane]; all += x; if (w2 < r) off += x; }
;             float bt[4], kt[4], vt[4];
; #pragma unroll
;             for (int i = 0; i < 4; ++i) {
;                 const float rc = dir ? xr[4 - i] : xr[1 + i], rp = dir ? xr[3 - i] : xr[i], rn = dir ? xr[5 - i] : xr[2 + i];
;                 const float kc = dir ? xk[4 - i] : xk[1 + i], kp = dir ? xk[3 - i] : xk[i], kn = dir ? xk[5 - i] : xk[2 + i];
;                 const float vc = dir ? xv[4 - i] : xv[1 + i], vp = dir ? xv[3 - i] : xv[i], vn = dir ? xv[5 - i] : xv[2 + i];
;                 const float rr = rc + mpr * (rp - rc) + mnr * (rn - rc);
;                 const float k = kc + mpk * (kp - kc) + mnk * (kn - kc);
;                 const float v = vc + mpv * (vp - vc) + mnv * (vn - vc);
;                 const float av = bf2f(rawA[i]);
;                 const float cum = cl[i] + off;
;                 const float Pin = __expf(cum), Pprev = __expf(cum - Lv[i]), Pinv = __expf(-cum);
;                 const float kk = k * kkc * rawS[i];
;                 const float bb = kk * av * Pinv, kd = k * (1.0f + (av - 1.0f) * kac) * Pinv;
;                 const int tau = 4 * r + i;
;                 At[tau * 72 + lane] = (bf16_t)f2bf(-kk * Pprev); Rt[tau * 72 + lane] = (bf16_t)f2bf(rr * Pin); Bs[tau * 72 + lane] = (bf16_t)f2bf(bb); Ks[tau * 72 + lane] = (bf16_t)f2bf(kd);
	v_add_u32_e32 v45, s84, v16
	ds_read2st64_b32 v[16:17], v45 offset0:92 offset1:93
	v_lshlrev_b32_e32 v20, 16, v144
	s_waitcnt vmcnt(5)
	v_lshlrev_b32_e32 v21, 16, v146
	v_cndmask_b32_e32 v46, 0, v20, vcc
	v_cndmask_b32_e32 v47, 0, v21, vcc
	ds_read2st64_b32 v[20:21], v45 offset0:94 offset1:95
	s_waitcnt vmcnt(4)
	v_lshlrev_b32_e32 v22, 16, v148
	s_waitcnt lgkmcnt(1)
	v_add_f32_e32 v16, 0, v16
	v_cndmask_b32_e32 v48, 0, v22, vcc
	v_cndmask_b32_e64 v22, v16, 0, s[6:7]
	v_add_f32_e32 v23, v17, v22
	v_cndmask_b32_e64 v22, v22, v23, s[12:13]
	s_waitcnt lgkmcnt(0)
	v_add_f32_e32 v23, v20, v22
	v_cndmask_b32_e64 v49, v22, v23, s[14:15]
	v_cndmask_b32_e64 v50, v35, v26, s[8:9]
	v_cndmask_b32_e64 v22, v32, v24, s[8:9]
	v_cndmask_b32_e64 v23, v46, v29, s[8:9]
	v_cndmask_b32_e64 v133, v36, v27, s[8:9]
	v_cndmask_b32_e64 v51, v33, v25, s[8:9]
	v_sub_f32_e32 v22, v22, v50
	v_cndmask_b32_e64 v52, v47, v30, s[8:9]
	v_cndmask_b32_e64 v53, v37, v28, s[8:9]
	v_cndmask_b32_e64 v54, v34, v18, s[8:9]
	v_sub_f32_e32 v23, v23, v50
	v_fmac_f32_e32 v50, v120, v22
	v_sub_f32_e32 v22, v51, v133
	v_cndmask_b32_e64 v55, v48, v31, s[8:9]
	v_fmac_f32_e32 v50, v121, v23
	v_sub_f32_e32 v23, v52, v133
	v_fmac_f32_e32 v133, v122, v22
	v_sub_f32_e32 v22, v54, v53
	v_sub_f32_e32 v51, v55, v53
	v_fmac_f32_e32 v53, v118, v22
	v_add_f32_e32 v22, v49, v38
	v_fmac_f32_e32 v53, v119, v51
	v_lshlrev_b32_e32 v51, 16, v147
	v_mul_f32_e32 v52, 0x3fb8aa3b, v22
	v_sub_f32_e32 v38, v22, v38
	v_mul_f32_e32 v22, 0xbfb8aa3b, v22
	v_mul_f32_e32 v38, 0x3fb8aa3b, v38
	v_exp_f32_e32 v54, v22
	v_add_f32_e32 v22, -1.0, v51
	v_exp_f32_e32 v38, v38
	v_pk_fma_f32 v[22:23], v[82:83], v[22:23], v[132:133]
	v_exp_f32_e32 v52, v52
	v_mul_f32_e32 v55, v123, v23
	s_waitcnt vmcnt(3)
	v_mul_f32_e32 v55, v149, v55
	v_mul_f32_e32 v51, v55, v51
	v_mul_f32_e32 v22, v22, v23
	v_mul_f32_e32 v51, v54, v51
	v_mul_f32_e32 v54, v22, v54
	v_mul_f32_e64 v22, v38, -v55
	v_cvt_pk_bf16_f32 v22, v22, s0
	v_lshl_add_u32 v38, v94, 1, s84
	ds_write_b16 v38, v22
	v_mul_f32_e32 v22, v50, v52
	v_cvt_pk_bf16_f32 v22, v22, s0
	ds_write_b16 v38, v22 offset:2304
	v_cvt_pk_bf16_f32 v22, v51, s0
	ds_write_b16 v38, v22 offset:4608
	v_cvt_pk_bf16_f32 v22, v54, s0
	ds_write_b16 v38, v22 offset:6912
	v_cndmask_b32_e64 v50, v32, v29, s[8:9]
	v_cndmask_b32_e64 v22, v29, v26, s[8:9]
	v_cndmask_b32_e64 v23, v35, v32, s[8:9]
	v_cndmask_b32_e64 v133, v33, v30, s[8:9]
	v_cndmask_b32_e64 v52, v30, v27, s[8:9]
	v_sub_f32_e32 v22, v22, v50
	v_cndmask_b32_e64 v55, v36, v33, s[8:9]
	v_cndmask_b32_e64 v56, v34, v31, s[8:9]
	v_cndmask_b32_e64 v57, v31, v28, s[8:9]
	v_sub_f32_e32 v23, v23, v50
	v_fmac_f32_e32 v50, v120, v22
	v_sub_f32_e32 v22, v52, v133
	v_cndmask_b32_e64 v58, v37, v34, s[8:9]
	v_fmac_f32_e32 v50, v121, v23
	v_sub_f32_e32 v23, v55, v133
	v_fmac_f32_e32 v133, v122, v22
	v_sub_f32_e32 v22, v57, v56
	v_sub_f32_e32 v52, v58, v56
	v_fmac_f32_e32 v56, v118, v22
	v_add_f32_e32 v22, v40, v49
	v_fmac_f32_e32 v56, v119, v52
	v_lshlrev_b32_e32 v52, 16, v151
	v_mul_f32_e32 v40, 0x3fb8aa3b, v22
	v_sub_f32_e32 v39, v22, v39
	v_mul_f32_e32 v22, 0xbfb8aa3b, v22
	v_mul_f32_e32 v39, 0x3fb8aa3b, v39
	v_exp_f32_e32 v55, v22
	v_add_f32_e32 v22, -1.0, v52
	v_exp_f32_e32 v39, v39
	v_pk_fma_f32 v[22:23], v[82:83], v[22:23], v[132:133]
	v_exp_f32_e32 v40, v40
	v_mul_f32_e32 v57, v123, v23
	s_waitcnt vmcnt(2)
; #define LAS __attribute__((address_space(3)))
; __device__ __forceinline__ unsigned pk2(float lo, float hi) { const f32x2 v = {lo, hi}; return __builtin_bit_cast(unsigned, __builtin_convertvector(v, bf16x2_t)); }
; __device__ __forceinline__ unsigned f2bf(float f) { return pk2(f, f) & 0xffffu; }
; #define BAR_LDS() do { asm volatile("s_waitcnt lgkmcnt(0)" ::: "memory"); __builtin_amdgcn_s_barrier(); asm volatile("" ::: "memory"); } while (0)
; __device__ __forceinline__ void scan2_phase(KA a, LAS unsigned char* lds, int G, const int tid, const int bid) {
;     ...
;             for (int i = 0; i < 4; ++i) {
;                 const float rc = dir ? xr[4 - i] : xr[1 + i], rp = dir ? xr[3 - i] : xr[i], rn = dir ? xr[5 - i] : xr[2 + i];
;                 const float kc = dir ? xk[4 - i] : xk[1 + i], kp = dir ? xk[3 - i] : xk[i], kn = dir ? xk[5 - i] : xk[2 + i];
;                 const float vc = dir ? xv[4 - i] : xv[1 + i], vp = dir ? xv[3 - i] : xv[i], vn = dir ? xv[5 - i] : xv[2 + i];
;                 const float rr = rc + mpr * (rp - rc) + mnr * (rn - rc);
;                 const float k = kc + mpk * (kp - kc) + mnk * (kn - kc);
;                 const float v = vc + mpv * (vp - vc) + mnv * (vn - vc);
;                 const float av = bf2f(rawA[i]);
;                 const float cum = cl[i] + off;
;                 const float Pin = __expf(cum), Pprev = __expf(cum - Lv[i]), Pinv = __expf(-cum);
;                 const float kk = k * kkc * rawS[i];
;                 const float bb = kk * av * Pinv, kd = k * (1.0f + (av - 1.0f) * kac) * Pinv;
;                 const int tau = 4 * r + i;
;                 At[tau * 72 + lane] = (bf16_t)f2bf(-kk * Pprev); Rt[tau * 72 + lane] = (bf16_t)f2bf(rr * Pin); Bs[tau * 72 + lane] = (bf16_t)f2bf(bb); Ks[tau * 72 + lane] = (bf16_t)f2bf(kd);
;                 bt[i] = bb; kt[i] = kd; vt[i] = v;
;             }
;             { u32x2 w; w.x = pk2(bt[0], bt[1]); w.y = pk2(bt[2], bt[3]); *(LAS u32x2*)(BT + lane * 24 + 4 * r) = w; }
;             { u32x2 w; w.x = pk2(kt[0], kt[1]); w.y = pk2(kt[2], kt[3]); *(LAS u32x2*)(KT + lane * 24 + 4 * r) = w; }
;             { u32x2 w; w.x = pk2(vt[0], vt[1]); w.y = pk2(vt[2], vt[3]); *(LAS u32x2*)(VT + lane * 24 + 4 * r) = w; }
;             if (r == 0) Pc[lane] = __expf(all);
;             if (b + 1 < nb) SC2_LOAD(b + 1);
;             BAR_LDS();
	v_mul_f32_e32 v57, v152, v57
	v_mul_f32_e32 v52, v57, v52
	v_mul_f32_e32 v22, v22, v23
	v_mul_f32_e32 v52, v55, v52
	v_mul_f32_e32 v55, v22, v55
	v_mul_f32_e64 v22, v39, -v57
	v_cvt_pk_bf16_f32 v22, v22, s0
	ds_write_b16 v38, v22 offset:144
	v_mul_f32_e32 v22, v50, v40
	v_cvt_pk_bf16_f32 v22, v22, s0
	ds_write_b16 v38, v22 offset:2448
	v_cvt_pk_bf16_f32 v22, v52, s0
	ds_write_b16 v38, v22 offset:4752
	v_cvt_pk_bf16_f32 v22, v55, s0
	ds_write_b16 v38, v22 offset:7056
	v_cndmask_b32_e64 v39, v29, v32, s[8:9]
	v_cndmask_b32_e64 v22, v26, v29, s[8:9]
	v_cndmask_b32_e64 v23, v32, v35, s[8:9]
	v_cndmask_b32_e64 v133, v30, v33, s[8:9]
	v_cndmask_b32_e64 v40, v27, v30, s[8:9]
	v_sub_f32_e32 v22, v22, v39
	v_cndmask_b32_e64 v50, v33, v36, s[8:9]
	v_cndmask_b32_e64 v57, v31, v34, s[8:9]
	v_cndmask_b32_e64 v58, v28, v31, s[8:9]
	v_sub_f32_e32 v23, v23, v39
	v_fmac_f32_e32 v39, v120, v22
	v_sub_f32_e32 v22, v40, v133
	v_cndmask_b32_e64 v59, v34, v37, s[8:9]
	v_fmac_f32_e32 v39, v121, v23
	v_sub_f32_e32 v23, v50, v133
	v_fmac_f32_e32 v133, v122, v22
	v_sub_f32_e32 v22, v58, v57
	v_sub_f32_e32 v40, v59, v57
	v_fmac_f32_e32 v57, v118, v22
	v_add_f32_e32 v22, v42, v49
	v_fmac_f32_e32 v57, v119, v40
	v_lshlrev_b32_e32 v40, 16, v154
	v_mul_f32_e32 v42, 0x3fb8aa3b, v22
	v_sub_f32_e32 v41, v22, v41
	v_mul_f32_e32 v22, 0xbfb8aa3b, v22
	v_mul_f32_e32 v41, 0x3fb8aa3b, v41
	v_exp_f32_e32 v50, v22
	v_add_f32_e32 v22, -1.0, v40
	v_exp_f32_e32 v41, v41
	v_pk_fma_f32 v[22:23], v[82:83], v[22:23], v[132:133]
	v_exp_f32_e32 v42, v42
	v_mul_f32_e32 v58, v123, v23
	s_waitcnt vmcnt(1)
	v_mul_f32_e32 v58, v155, v58
	v_mul_f32_e32 v40, v58, v40
	v_mul_f32_e32 v22, v22, v23
	v_mul_f32_e32 v40, v50, v40
	v_mul_f32_e32 v50, v22, v50
	v_mul_f32_e64 v22, v41, -v58
	v_cvt_pk_bf16_f32 v22, v22, s0
	ds_write_b16 v38, v22 offset:288
	v_mul_f32_e32 v22, v39, v42
	v_cvt_pk_bf16_f32 v22, v22, s0
	ds_write_b16 v38, v22 offset:2592
	v_cvt_pk_bf16_f32 v22, v40, s0
	ds_write_b16 v38, v22 offset:4896
	v_cvt_pk_bf16_f32 v22, v50, s0
	ds_write_b16 v38, v22 offset:7200
	v_cndmask_b32_e64 v26, v26, v35, s[8:9]
	v_cndmask_b32_e64 v22, v24, v32, s[8:9]
	v_cndmask_b32_e64 v23, v29, v46, s[8:9]
	v_cndmask_b32_e64 v133, v27, v36, s[8:9]
	v_cndmask_b32_e64 v24, v25, v33, s[8:9]
	v_cndmask_b32_e64 v27, v28, v37, s[8:9]
	v_cndmask_b32_e64 v18, v18, v34, s[8:9]
	v_sub_f32_e32 v22, v22, v26
	v_cndmask_b32_e64 v25, v30, v47, s[8:9]
	v_cndmask_b32_e64 v28, v31, v48, s[8:9]
	v_sub_f32_e32 v23, v23, v26
	v_fmac_f32_e32 v26, v120, v22
	v_sub_f32_e32 v22, v24, v133
	v_sub_f32_e32 v18, v18, v27
	v_fmac_f32_e32 v26, v121, v23
	v_sub_f32_e32 v23, v25, v133
	v_fmac_f32_e32 v133, v122, v22
	v_sub_f32_e32 v22, v28, v27
	v_fmac_f32_e32 v27, v118, v18
	v_fmac_f32_e32 v27, v119, v22
	v_add_f32_e32 v22, v44, v49
	v_lshlrev_b32_e32 v18, 16, v157
	v_mul_f32_e32 v24, 0x3fb8aa3b, v22
	v_sub_f32_e32 v25, v22, v43
	v_mul_f32_e32 v22, 0xbfb8aa3b, v22
	v_mul_f32_e32 v25, 0x3fb8aa3b, v25
	v_exp_f32_e32 v28, v22
	v_add_f32_e32 v22, -1.0, v18
	v_exp_f32_e32 v25, v25
	v_pk_fma_f32 v[22:23], v[82:83], v[22:23], v[132:133]
	v_exp_f32_e32 v24, v24
	v_mul_f32_e32 v29, v123, v23
	s_waitcnt vmcnt(0)
	v_mul_f32_e32 v29, v158, v29
	v_mul_f32_e32 v18, v29, v18
	v_mul_f32_e32 v22, v22, v23
	v_mul_f32_e32 v18, v28, v18
	v_mul_f32_e32 v28, v22, v28
	v_mul_f32_e64 v22, v25, -v29
	v_cvt_pk_bf16_f32 v22, v22, s0
	ds_write_b16 v38, v22 offset:432
	v_mul_f32_e32 v22, v26, v24
	v_cvt_pk_bf16_f32 v22, v22, s0
	ds_write_b16 v38, v22 offset:2736
	v_cvt_pk_bf16_f32 v22, v18, s0
	ds_write_b16 v38, v22 offset:5040
	v_cvt_pk_bf16_f32 v22, v28, s0
	v_cvt_pk_bf16_f32 v23, v40, v18
	v_add_u32_e32 v18, v45, v113
	ds_write_b16 v38, v22 offset:7344
	v_cvt_pk_bf16_f32 v22, v51, v52
	v_lshl_add_u32 v26, s66, 1, v18
	v_cvt_pk_bf16_f32 v24, v54, v55
	v_cvt_pk_bf16_f32 v25, v50, v28
	ds_write2st64_b64 v26, v[22:23], v[24:25] offset0:18 offset1:24
	v_cvt_pk_bf16_f32 v22, v53, v56
	v_cvt_pk_bf16_f32 v23, v57, v27
	s_andn2_b64 vcc, exec, s[6:7]
	ds_write_b64 v26, v[22:23] offset:15360
	s_cbranch_vccz .LBB0_186
	s_add_i32 s83, s83, 1
	s_cmp_ge_u32 s83, s82
	s_cbranch_scc1 .LBB0_184
